# v16 + attention PV tails: interleaved dependent MFMA quads (x,y,x,y) made adjacent chains (x,x,y,y)
# baseline (speedup 1.0000x reference)
.LBB0_343:
	s_andn2_b64 vcc, exec, s[2:3]
	s_cbranch_vccnz .LBB0_331
	v_add_u32_e32 v2, s21, v150
	v_cvt_pk_bf16_f32 v120, v120, v121
	v_cvt_pk_bf16_f32 v121, v4, v5
	v_cvt_pk_bf16_f32 v122, v122, v123
	v_cvt_pk_bf16_f32 v123, v124, v125
	v_cvt_pk_bf16_f32 v124, v134, v135
	v_cvt_pk_bf16_f32 v125, v126, v127
	v_cvt_pk_bf16_f32 v126, v138, v139
	v_cvt_pk_bf16_f32 v127, v136, v137
	ds_read_b64_tr_b16 v[134:135], v2 offset:0
	ds_read_b64_tr_b16 v[136:137], v2 offset:0x2200
	ds_read_b64_tr_b16 v[178:179], v2 offset:0x4400
	ds_read_b64_tr_b16 v[180:181], v2 offset:0x6600
	ds_read_b64_tr_b16 v[182:183], v2 offset:32
	ds_read_b64_tr_b16 v[184:185], v2 offset:0x2220
	ds_read_b64_tr_b16 v[186:187], v2 offset:0x4420
	ds_read_b64_tr_b16 v[188:189], v2 offset:0x6620
	ds_read_b64_tr_b16 v[190:191], v2 offset:64
	ds_read_b64_tr_b16 v[192:193], v2 offset:0x2240
	ds_read_b64_tr_b16 v[194:195], v2 offset:0x4440
	ds_read_b64_tr_b16 v[196:197], v2 offset:0x6640
	ds_read_b64_tr_b16 v[208:209], v2 offset:0x60
	ds_read_b64_tr_b16 v[210:211], v2 offset:0x2260
	ds_read_b64_tr_b16 v[212:213], v2 offset:0x4460
	ds_read_b64_tr_b16 v[214:215], v2 offset:0x6660
	s_waitcnt lgkmcnt(8)
	s_nop 0
	v_mfma_f32_16x16x32_bf16 v[68:71], v[120:123], v[134:137], v[68:71]
	ds_read_b64_tr_b16 v[134:135], v2 offset:0x80
	ds_read_b64_tr_b16 v[136:137], v2 offset:0x2280
	v_mfma_f32_16x16x32_bf16 v[68:71], v[124:127], v[178:181], v[68:71]
	ds_read_b64_tr_b16 v[178:179], v2 offset:0x4480
	ds_read_b64_tr_b16 v[180:181], v2 offset:0x6680
	v_mfma_f32_16x16x32_bf16 v[64:67], v[120:123], v[182:185], v[64:67]
	ds_read_b64_tr_b16 v[182:183], v2 offset:0xa0
	ds_read_b64_tr_b16 v[184:185], v2 offset:0x22a0
	v_mfma_f32_16x16x32_bf16 v[64:67], v[124:127], v[186:189], v[64:67]
	ds_read_b64_tr_b16 v[186:187], v2 offset:0x44a0
	ds_read_b64_tr_b16 v[188:189], v2 offset:0x66a0
	s_waitcnt lgkmcnt(8)
	v_mfma_f32_16x16x32_bf16 v[60:63], v[120:123], v[190:193], v[60:63]
	ds_read_b64_tr_b16 v[190:191], v2 offset:0xc0
	ds_read_b64_tr_b16 v[192:193], v2 offset:0x22c0
	v_mfma_f32_16x16x32_bf16 v[60:63], v[124:127], v[194:197], v[60:63]
	ds_read_b64_tr_b16 v[194:195], v2 offset:0x44c0
	ds_read_b64_tr_b16 v[196:197], v2 offset:0x66c0
	v_mfma_f32_16x16x32_bf16 v[56:59], v[120:123], v[208:211], v[56:59]
	ds_read_b64_tr_b16 v[208:209], v2 offset:0xe0
	ds_read_b64_tr_b16 v[210:211], v2 offset:0x22e0
	v_mfma_f32_16x16x32_bf16 v[56:59], v[124:127], v[212:215], v[56:59]
	ds_read_b64_tr_b16 v[212:213], v2 offset:0x44e0
	ds_read_b64_tr_b16 v[214:215], v2 offset:0x66e0
	s_waitcnt lgkmcnt(8)
	v_mfma_f32_16x16x32_bf16 v[52:55], v[120:123], v[134:137], v[52:55]
	ds_read_b64_tr_b16 v[134:135], v2 offset:0x100
	ds_read_b64_tr_b16 v[136:137], v2 offset:0x2300
	v_mfma_f32_16x16x32_bf16 v[52:55], v[124:127], v[178:181], v[52:55]
	ds_read_b64_tr_b16 v[178:179], v2 offset:0x4500
	ds_read_b64_tr_b16 v[180:181], v2 offset:0x6700
	v_mfma_f32_16x16x32_bf16 v[48:51], v[120:123], v[182:185], v[48:51]
	ds_read_b64_tr_b16 v[182:183], v2 offset:0x120
	ds_read_b64_tr_b16 v[184:185], v2 offset:0x2320
	v_mfma_f32_16x16x32_bf16 v[48:51], v[124:127], v[186:189], v[48:51]
	ds_read_b64_tr_b16 v[186:187], v2 offset:0x4520
	ds_read_b64_tr_b16 v[188:189], v2 offset:0x6720
	s_waitcnt lgkmcnt(8)
	v_mfma_f32_16x16x32_bf16 v[44:47], v[120:123], v[190:193], v[44:47]
	ds_read_b64_tr_b16 v[190:191], v2 offset:0x140
	ds_read_b64_tr_b16 v[192:193], v2 offset:0x2340
	v_mfma_f32_16x16x32_bf16 v[44:47], v[124:127], v[194:197], v[44:47]
	ds_read_b64_tr_b16 v[194:195], v2 offset:0x4540
	ds_read_b64_tr_b16 v[196:197], v2 offset:0x6740
	v_mfma_f32_16x16x32_bf16 v[40:43], v[120:123], v[208:211], v[40:43]
	ds_read_b64_tr_b16 v[208:209], v2 offset:0x160
	ds_read_b64_tr_b16 v[210:211], v2 offset:0x2360
	v_mfma_f32_16x16x32_bf16 v[40:43], v[124:127], v[212:215], v[40:43]
	ds_read_b64_tr_b16 v[212:213], v2 offset:0x4560
	ds_read_b64_tr_b16 v[214:215], v2 offset:0x6760
	s_waitcnt lgkmcnt(8)
	v_mfma_f32_16x16x32_bf16 v[36:39], v[120:123], v[134:137], v[36:39]
	ds_read_b64_tr_b16 v[134:135], v2 offset:0x180
	ds_read_b64_tr_b16 v[136:137], v2 offset:0x2380
	v_mfma_f32_16x16x32_bf16 v[36:39], v[124:127], v[178:181], v[36:39]
	ds_read_b64_tr_b16 v[178:179], v2 offset:0x4580
	ds_read_b64_tr_b16 v[180:181], v2 offset:0x6780
	v_mfma_f32_16x16x32_bf16 v[32:35], v[120:123], v[182:185], v[32:35]
	ds_read_b64_tr_b16 v[182:183], v2 offset:0x1a0
	ds_read_b64_tr_b16 v[184:185], v2 offset:0x23a0
	v_mfma_f32_16x16x32_bf16 v[32:35], v[124:127], v[186:189], v[32:35]
	ds_read_b64_tr_b16 v[186:187], v2 offset:0x45a0
	ds_read_b64_tr_b16 v[188:189], v2 offset:0x67a0
	s_waitcnt lgkmcnt(8)
	v_mfma_f32_16x16x32_bf16 v[28:31], v[120:123], v[190:193], v[28:31]
	ds_read_b64_tr_b16 v[190:191], v2 offset:0x1c0
	ds_read_b64_tr_b16 v[192:193], v2 offset:0x23c0
	v_mfma_f32_16x16x32_bf16 v[28:31], v[124:127], v[194:197], v[28:31]
	ds_read_b64_tr_b16 v[194:195], v2 offset:0x45c0
	ds_read_b64_tr_b16 v[196:197], v2 offset:0x67c0
	v_mfma_f32_16x16x32_bf16 v[24:27], v[120:123], v[208:211], v[24:27]
	ds_read_b64_tr_b16 v[208:209], v2 offset:0x1e0
	ds_read_b64_tr_b16 v[210:211], v2 offset:0x23e0
	v_mfma_f32_16x16x32_bf16 v[24:27], v[124:127], v[212:215], v[24:27]
	ds_read_b64_tr_b16 v[212:213], v2 offset:0x45e0
	ds_read_b64_tr_b16 v[214:215], v2 offset:0x67e0
	s_waitcnt lgkmcnt(8)
	v_mfma_f32_16x16x32_bf16 v[20:23], v[120:123], v[134:137], v[20:23]
	s_waitcnt lgkmcnt(0)
	v_mfma_f32_16x16x32_bf16 v[20:23], v[124:127], v[178:181], v[20:23]
	v_mfma_f32_16x16x32_bf16 v[16:19], v[120:123], v[182:185], v[16:19]
	v_mfma_f32_16x16x32_bf16 v[16:19], v[124:127], v[186:189], v[16:19]
	v_mfma_f32_16x16x32_bf16 v[12:15], v[120:123], v[190:193], v[12:15]
	v_mfma_f32_16x16x32_bf16 v[12:15], v[124:127], v[194:197], v[12:15]
	v_mfma_f32_16x16x32_bf16 v[8:11], v[120:123], v[208:211], v[8:11]
	v_mfma_f32_16x16x32_bf16 v[8:11], v[124:127], v[212:215], v[8:11]
	s_branch .LBB0_331

.LBB0_354:
	s_andn2_b64 vcc, exec, s[2:3]
	s_cbranch_vccnz .LBB0_356
	v_add_u32_e32 v2, s7, v150
	v_cvt_pk_bf16_f32 v72, v72, v73
	v_cvt_pk_bf16_f32 v73, v4, v5
	v_cvt_pk_bf16_f32 v74, v74, v75
	v_cvt_pk_bf16_f32 v75, v76, v77
	v_cvt_pk_bf16_f32 v76, v80, v81
	v_cvt_pk_bf16_f32 v77, v78, v79
	v_cvt_pk_bf16_f32 v78, v84, v85
	v_cvt_pk_bf16_f32 v79, v82, v83
	ds_read_b64_tr_b16 v[80:81], v2 offset:0
	ds_read_b64_tr_b16 v[82:83], v2 offset:0x2200
	ds_read_b64_tr_b16 v[84:85], v2 offset:0x4400
	ds_read_b64_tr_b16 v[86:87], v2 offset:0x6600
	ds_read_b64_tr_b16 v[88:89], v2 offset:32
	ds_read_b64_tr_b16 v[90:91], v2 offset:0x2220
	ds_read_b64_tr_b16 v[92:93], v2 offset:0x4420
	ds_read_b64_tr_b16 v[94:95], v2 offset:0x6620
	ds_read_b64_tr_b16 v[96:97], v2 offset:64
	ds_read_b64_tr_b16 v[98:99], v2 offset:0x2240
	ds_read_b64_tr_b16 v[100:101], v2 offset:0x4440
	ds_read_b64_tr_b16 v[102:103], v2 offset:0x6640
	ds_read_b64_tr_b16 v[104:105], v2 offset:0x60
	ds_read_b64_tr_b16 v[106:107], v2 offset:0x2260
	ds_read_b64_tr_b16 v[108:109], v2 offset:0x4460
	ds_read_b64_tr_b16 v[110:111], v2 offset:0x6660
	s_waitcnt lgkmcnt(8)
	s_nop 0
	v_mfma_f32_16x16x32_bf16 v[68:71], v[72:75], v[80:83], v[68:71]
	ds_read_b64_tr_b16 v[80:81], v2 offset:0x80
	ds_read_b64_tr_b16 v[82:83], v2 offset:0x2280
	v_mfma_f32_16x16x32_bf16 v[68:71], v[76:79], v[84:87], v[68:71]
	ds_read_b64_tr_b16 v[84:85], v2 offset:0x4480
	ds_read_b64_tr_b16 v[86:87], v2 offset:0x6680
	v_mfma_f32_16x16x32_bf16 v[64:67], v[72:75], v[88:91], v[64:67]
	ds_read_b64_tr_b16 v[88:89], v2 offset:0xa0
	ds_read_b64_tr_b16 v[90:91], v2 offset:0x22a0
	v_mfma_f32_16x16x32_bf16 v[64:67], v[76:79], v[92:95], v[64:67]
	ds_read_b64_tr_b16 v[92:93], v2 offset:0x44a0
	ds_read_b64_tr_b16 v[94:95], v2 offset:0x66a0
	s_waitcnt lgkmcnt(8)
	v_mfma_f32_16x16x32_bf16 v[60:63], v[72:75], v[96:99], v[60:63]
	ds_read_b64_tr_b16 v[96:97], v2 offset:0xc0
	ds_read_b64_tr_b16 v[98:99], v2 offset:0x22c0
	v_mfma_f32_16x16x32_bf16 v[60:63], v[76:79], v[100:103], v[60:63]
	ds_read_b64_tr_b16 v[100:101], v2 offset:0x44c0
	ds_read_b64_tr_b16 v[102:103], v2 offset:0x66c0
	v_mfma_f32_16x16x32_bf16 v[56:59], v[72:75], v[104:107], v[56:59]
	ds_read_b64_tr_b16 v[104:105], v2 offset:0xe0
	ds_read_b64_tr_b16 v[106:107], v2 offset:0x22e0
	v_mfma_f32_16x16x32_bf16 v[56:59], v[76:79], v[108:111], v[56:59]
	ds_read_b64_tr_b16 v[108:109], v2 offset:0x44e0
	ds_read_b64_tr_b16 v[110:111], v2 offset:0x66e0
	s_waitcnt lgkmcnt(8)
	v_mfma_f32_16x16x32_bf16 v[52:55], v[72:75], v[80:83], v[52:55]
	ds_read_b64_tr_b16 v[80:81], v2 offset:0x100
	ds_read_b64_tr_b16 v[82:83], v2 offset:0x2300
	v_mfma_f32_16x16x32_bf16 v[52:55], v[76:79], v[84:87], v[52:55]
	ds_read_b64_tr_b16 v[84:85], v2 offset:0x4500
	ds_read_b64_tr_b16 v[86:87], v2 offset:0x6700
	v_mfma_f32_16x16x32_bf16 v[48:51], v[72:75], v[88:91], v[48:51]
	ds_read_b64_tr_b16 v[88:89], v2 offset:0x120
	ds_read_b64_tr_b16 v[90:91], v2 offset:0x2320
	v_mfma_f32_16x16x32_bf16 v[48:51], v[76:79], v[92:95], v[48:51]
	ds_read_b64_tr_b16 v[92:93], v2 offset:0x4520
	ds_read_b64_tr_b16 v[94:95], v2 offset:0x6720
	s_waitcnt lgkmcnt(8)
	v_mfma_f32_16x16x32_bf16 v[44:47], v[72:75], v[96:99], v[44:47]
	ds_read_b64_tr_b16 v[96:97], v2 offset:0x140
	ds_read_b64_tr_b16 v[98:99], v2 offset:0x2340
	v_mfma_f32_16x16x32_bf16 v[44:47], v[76:79], v[100:103], v[44:47]
	ds_read_b64_tr_b16 v[100:101], v2 offset:0x4540
	ds_read_b64_tr_b16 v[102:103], v2 offset:0x6740
	v_mfma_f32_16x16x32_bf16 v[40:43], v[72:75], v[104:107], v[40:43]
	ds_read_b64_tr_b16 v[104:105], v2 offset:0x160
	ds_read_b64_tr_b16 v[106:107], v2 offset:0x2360
	v_mfma_f32_16x16x32_bf16 v[40:43], v[76:79], v[108:111], v[40:43]
	ds_read_b64_tr_b16 v[108:109], v2 offset:0x4560
	ds_read_b64_tr_b16 v[110:111], v2 offset:0x6760
	s_waitcnt lgkmcnt(8)
	v_mfma_f32_16x16x32_bf16 v[36:39], v[72:75], v[80:83], v[36:39]
	ds_read_b64_tr_b16 v[80:81], v2 offset:0x180
	ds_read_b64_tr_b16 v[82:83], v2 offset:0x2380
	v_mfma_f32_16x16x32_bf16 v[36:39], v[76:79], v[84:87], v[36:39]
	ds_read_b64_tr_b16 v[84:85], v2 offset:0x4580
	ds_read_b64_tr_b16 v[86:87], v2 offset:0x6780
	v_mfma_f32_16x16x32_bf16 v[32:35], v[72:75], v[88:91], v[32:35]
	ds_read_b64_tr_b16 v[88:89], v2 offset:0x1a0
	ds_read_b64_tr_b16 v[90:91], v2 offset:0x23a0
	v_mfma_f32_16x16x32_bf16 v[32:35], v[76:79], v[92:95], v[32:35]
	ds_read_b64_tr_b16 v[92:93], v2 offset:0x45a0
	ds_read_b64_tr_b16 v[94:95], v2 offset:0x67a0
	s_waitcnt lgkmcnt(8)
	v_mfma_f32_16x16x32_bf16 v[28:31], v[72:75], v[96:99], v[28:31]
	ds_read_b64_tr_b16 v[96:97], v2 offset:0x1c0
	ds_read_b64_tr_b16 v[98:99], v2 offset:0x23c0
	v_mfma_f32_16x16x32_bf16 v[28:31], v[76:79], v[100:103], v[28:31]
	ds_read_b64_tr_b16 v[100:101], v2 offset:0x45c0
	ds_read_b64_tr_b16 v[102:103], v2 offset:0x67c0
	v_mfma_f32_16x16x32_bf16 v[24:27], v[72:75], v[104:107], v[24:27]
	ds_read_b64_tr_b16 v[104:105], v2 offset:0x1e0
	ds_read_b64_tr_b16 v[106:107], v2 offset:0x23e0
	v_mfma_f32_16x16x32_bf16 v[24:27], v[76:79], v[108:111], v[24:27]
	ds_read_b64_tr_b16 v[108:109], v2 offset:0x45e0
	ds_read_b64_tr_b16 v[110:111], v2 offset:0x67e0
	s_waitcnt lgkmcnt(8)
	v_mfma_f32_16x16x32_bf16 v[20:23], v[72:75], v[80:83], v[20:23]
	s_waitcnt lgkmcnt(0)
	v_mfma_f32_16x16x32_bf16 v[20:23], v[76:79], v[84:87], v[20:23]
	v_mfma_f32_16x16x32_bf16 v[16:19], v[72:75], v[88:91], v[16:19]
	v_mfma_f32_16x16x32_bf16 v[16:19], v[76:79], v[92:95], v[16:19]
	v_mfma_f32_16x16x32_bf16 v[12:15], v[72:75], v[96:99], v[12:15]
	v_mfma_f32_16x16x32_bf16 v[12:15], v[76:79], v[100:103], v[12:15]
	v_mfma_f32_16x16x32_bf16 v[8:11], v[72:75], v[104:107], v[8:11]
	v_mfma_f32_16x16x32_bf16 v[8:11], v[76:79], v[108:111], v[8:11]

.LBB0_386:
	s_mul_i32 s7, s1, 0xd000
	s_mov_b32 s89, s1
	s_add_i32 s1, s7, 0
	s_add_i32 s2, s81, 0xffffff81
	v_add_u32_e32 v128, s1, v4
	s_ashr_i32 s3, s2, 31
	s_waitcnt lgkmcnt(0)
	s_barrier
	s_waitcnt vmcnt(5)
	ds_write_b128 v128, v[92:95]
	s_waitcnt vmcnt(4)
	ds_write_b128 v128, v[88:91] offset:128
	v_add_u32_e32 v88, s1, v178
	s_lshl_b64 s[2:3], s[2:3], 12
	s_waitcnt vmcnt(3)
	ds_write_b128 v88, v[96:99] offset:18432
	s_waitcnt vmcnt(2)
	ds_write_b128 v88, v[100:103] offset:18560
	s_waitcnt vmcnt(1)
	ds_write_b128 v88, v[104:107] offset:18688
	s_waitcnt vmcnt(0)
	ds_write_b128 v88, v[108:111] offset:18816
	v_lshl_add_u64 v[88:89], v[148:149], 0, s[2:3]
	v_lshl_add_u64 v[108:109], v[150:151], 0, s[2:3]
	global_load_dwordx4 v[92:95], v[88:89], off
	s_nop 0
	global_load_dwordx4 v[88:91], v[88:89], off offset:128
	s_nop 0
	global_load_dwordx4 v[96:99], v[108:109], off
	global_load_dwordx4 v[100:103], v[108:109], off offset:128
	global_load_dwordx4 v[104:107], v[108:109], off offset:256
	s_nop 0
	global_load_dwordx4 v[108:111], v[108:109], off offset:384
	s_mul_i32 s1, s55, 0xd000
	v_add_u32_e32 v147, s1, v169
	ds_read_b128 v[128:131], v147 offset:0
	ds_read_b128 v[132:135], v147 offset:64
	ds_read_b128 v[136:139], v147 offset:0x80
	ds_read_b128 v[140:143], v147 offset:0xc0
	ds_read_b128 v[154:157], v147 offset:0x1200
	ds_read_b128 v[158:161], v147 offset:0x1240
	ds_read_b128 v[194:197], v147 offset:0x1280
	ds_read_b128 v[208:211], v147 offset:0x12c0
	s_waitcnt lgkmcnt(4)
	s_nop 0
	v_mfma_f32_16x16x32_bf16 v[128:131], v[128:131], v[12:15], 0
	v_mfma_f32_16x16x32_bf16 v[128:131], v[132:135], v[16:19], v[128:131]
	v_mfma_f32_16x16x32_bf16 v[128:131], v[136:139], v[20:23], v[128:131]
	ds_read_b128 v[136:139], v147 offset:0x2400
	v_mfma_f32_16x16x32_bf16 v[128:131], v[140:143], v[8:11], v[128:131]
	ds_read_b128 v[140:143], v147 offset:0x2440
	ds_read_b128 v[214:217], v147 offset:0x2480
	ds_read_b128 v[218:221], v147 offset:0x24c0
	s_waitcnt lgkmcnt(4)
	v_mfma_f32_16x16x32_bf16 v[132:135], v[154:157], v[12:15], 0
	ds_read_b128 v[154:157], v147 offset:0x3600
	v_mfma_f32_16x16x32_bf16 v[132:135], v[158:161], v[16:19], v[132:135]
	ds_read_b128 v[158:161], v147 offset:0x3640
	v_mfma_f32_16x16x32_bf16 v[132:135], v[194:197], v[20:23], v[132:135]
	ds_read_b128 v[194:197], v147 offset:0x3680
	v_mfma_f32_16x16x32_bf16 v[132:135], v[208:211], v[8:11], v[132:135]
	ds_read_b128 v[208:211], v147 offset:0x36c0
	s_waitcnt lgkmcnt(4)
	v_mfma_f32_16x16x32_bf16 v[136:139], v[136:139], v[12:15], 0
	s_waitcnt lgkmcnt(0)
	v_mfma_f32_16x16x32_bf16 v[136:139], v[140:143], v[16:19], v[136:139]
	v_mfma_f32_16x16x32_bf16 v[136:139], v[214:217], v[20:23], v[136:139]
	v_mfma_f32_16x16x32_bf16 v[140:143], v[218:221], v[8:11], v[136:139]
	v_mfma_f32_16x16x32_bf16 v[136:139], v[154:157], v[12:15], 0
	s_and_b64 vcc, exec, s[44:45]
	s_mul_i32 s27, s88, 0xd000
	v_mfma_f32_16x16x32_bf16 v[136:139], v[158:161], v[16:19], v[136:139]
	v_mfma_f32_16x16x32_bf16 v[136:139], v[194:197], v[20:23], v[136:139]
	v_mfma_f32_16x16x32_bf16 v[136:139], v[208:211], v[8:11], v[136:139]
	s_cbranch_vccnz .LBB0_388
	s_mul_i32 s2, s88, 0xd000
	v_add_u32_e32 v147, s2, v167
	v_cvt_pk_bf16_f32 v112, v112, v113
	v_cvt_pk_bf16_f32 v113, v114, v115
	v_cvt_pk_bf16_f32 v114, v116, v117
	v_cvt_pk_bf16_f32 v115, v118, v119
	v_cvt_pk_bf16_f32 v116, v120, v121
	v_cvt_pk_bf16_f32 v117, v122, v123
	v_cvt_pk_bf16_f32 v118, v124, v125
	v_cvt_pk_bf16_f32 v119, v126, v127
	ds_read_b64_tr_b16 v[120:121], v147 offset:0
	ds_read_b64_tr_b16 v[122:123], v147 offset:0x2200
	ds_read_b64_tr_b16 v[124:125], v147 offset:0x4400
	ds_read_b64_tr_b16 v[126:127], v147 offset:0x6600
	ds_read_b64_tr_b16 v[154:155], v147 offset:32
	ds_read_b64_tr_b16 v[156:157], v147 offset:0x2220
	ds_read_b64_tr_b16 v[158:159], v147 offset:0x4420
	ds_read_b64_tr_b16 v[160:161], v147 offset:0x6620
	ds_read_b64_tr_b16 v[194:195], v147 offset:64
	ds_read_b64_tr_b16 v[196:197], v147 offset:0x2240
	ds_read_b64_tr_b16 v[208:209], v147 offset:0x4440
	ds_read_b64_tr_b16 v[210:211], v147 offset:0x6640
	ds_read_b64_tr_b16 v[214:215], v147 offset:0x60
	ds_read_b64_tr_b16 v[216:217], v147 offset:0x2260
	ds_read_b64_tr_b16 v[218:219], v147 offset:0x4460
	ds_read_b64_tr_b16 v[220:221], v147 offset:0x6660
	s_waitcnt lgkmcnt(8)
	s_nop 0
	v_mfma_f32_16x16x32_bf16 v[84:87], v[112:115], v[120:123], v[84:87]
	ds_read_b64_tr_b16 v[120:121], v147 offset:0x80
	ds_read_b64_tr_b16 v[122:123], v147 offset:0x2280
	v_mfma_f32_16x16x32_bf16 v[84:87], v[116:119], v[124:127], v[84:87]
	ds_read_b64_tr_b16 v[124:125], v147 offset:0x4480
	ds_read_b64_tr_b16 v[126:127], v147 offset:0x6680
	v_mfma_f32_16x16x32_bf16 v[80:83], v[112:115], v[154:157], v[80:83]
	ds_read_b64_tr_b16 v[154:155], v147 offset:0xa0
	ds_read_b64_tr_b16 v[156:157], v147 offset:0x22a0
	v_mfma_f32_16x16x32_bf16 v[80:83], v[116:119], v[158:161], v[80:83]
	ds_read_b64_tr_b16 v[158:159], v147 offset:0x44a0
	ds_read_b64_tr_b16 v[160:161], v147 offset:0x66a0
	s_waitcnt lgkmcnt(8)
	v_mfma_f32_16x16x32_bf16 v[76:79], v[112:115], v[194:197], v[76:79]
	ds_read_b64_tr_b16 v[194:195], v147 offset:0xc0
	ds_read_b64_tr_b16 v[196:197], v147 offset:0x22c0
	v_mfma_f32_16x16x32_bf16 v[76:79], v[116:119], v[208:211], v[76:79]
	ds_read_b64_tr_b16 v[208:209], v147 offset:0x44c0
	ds_read_b64_tr_b16 v[210:211], v147 offset:0x66c0
	v_mfma_f32_16x16x32_bf16 v[72:75], v[112:115], v[214:217], v[72:75]
	ds_read_b64_tr_b16 v[214:215], v147 offset:0xe0
	ds_read_b64_tr_b16 v[216:217], v147 offset:0x22e0
	v_mfma_f32_16x16x32_bf16 v[72:75], v[116:119], v[218:221], v[72:75]
	ds_read_b64_tr_b16 v[218:219], v147 offset:0x44e0
	ds_read_b64_tr_b16 v[220:221], v147 offset:0x66e0
	s_waitcnt lgkmcnt(8)
	v_mfma_f32_16x16x32_bf16 v[68:71], v[112:115], v[120:123], v[68:71]
	ds_read_b64_tr_b16 v[120:121], v147 offset:0x100
	ds_read_b64_tr_b16 v[122:123], v147 offset:0x2300
	v_mfma_f32_16x16x32_bf16 v[68:71], v[116:119], v[124:127], v[68:71]
	ds_read_b64_tr_b16 v[124:125], v147 offset:0x4500
	ds_read_b64_tr_b16 v[126:127], v147 offset:0x6700
	v_mfma_f32_16x16x32_bf16 v[64:67], v[112:115], v[154:157], v[64:67]
	ds_read_b64_tr_b16 v[154:155], v147 offset:0x120
	ds_read_b64_tr_b16 v[156:157], v147 offset:0x2320
	v_mfma_f32_16x16x32_bf16 v[64:67], v[116:119], v[158:161], v[64:67]
	ds_read_b64_tr_b16 v[158:159], v147 offset:0x4520
	ds_read_b64_tr_b16 v[160:161], v147 offset:0x6720
	s_waitcnt lgkmcnt(8)
	v_mfma_f32_16x16x32_bf16 v[60:63], v[112:115], v[194:197], v[60:63]
	ds_read_b64_tr_b16 v[194:195], v147 offset:0x140
	ds_read_b64_tr_b16 v[196:197], v147 offset:0x2340
	v_mfma_f32_16x16x32_bf16 v[60:63], v[116:119], v[208:211], v[60:63]
	ds_read_b64_tr_b16 v[208:209], v147 offset:0x4540
	ds_read_b64_tr_b16 v[210:211], v147 offset:0x6740
	v_mfma_f32_16x16x32_bf16 v[56:59], v[112:115], v[214:217], v[56:59]
	ds_read_b64_tr_b16 v[214:215], v147 offset:0x160
	ds_read_b64_tr_b16 v[216:217], v147 offset:0x2360
	v_mfma_f32_16x16x32_bf16 v[56:59], v[116:119], v[218:221], v[56:59]
	ds_read_b64_tr_b16 v[218:219], v147 offset:0x4560
	ds_read_b64_tr_b16 v[220:221], v147 offset:0x6760
	s_waitcnt lgkmcnt(8)
	v_mfma_f32_16x16x32_bf16 v[48:51], v[112:115], v[120:123], v[48:51]
	ds_read_b64_tr_b16 v[120:121], v147 offset:0x180
	ds_read_b64_tr_b16 v[122:123], v147 offset:0x2380
	v_mfma_f32_16x16x32_bf16 v[48:51], v[116:119], v[124:127], v[48:51]
	ds_read_b64_tr_b16 v[124:125], v147 offset:0x4580
	ds_read_b64_tr_b16 v[126:127], v147 offset:0x6780
	v_mfma_f32_16x16x32_bf16 v[40:43], v[112:115], v[154:157], v[40:43]
	ds_read_b64_tr_b16 v[154:155], v147 offset:0x1a0
	ds_read_b64_tr_b16 v[156:157], v147 offset:0x23a0
	v_mfma_f32_16x16x32_bf16 v[40:43], v[116:119], v[158:161], v[40:43]
	ds_read_b64_tr_b16 v[158:159], v147 offset:0x45a0
	ds_read_b64_tr_b16 v[160:161], v147 offset:0x67a0
	s_waitcnt lgkmcnt(8)
	v_mfma_f32_16x16x32_bf16 v[36:39], v[112:115], v[194:197], v[36:39]
	ds_read_b64_tr_b16 v[194:195], v147 offset:0x1c0
	ds_read_b64_tr_b16 v[196:197], v147 offset:0x23c0
	v_mfma_f32_16x16x32_bf16 v[36:39], v[116:119], v[208:211], v[36:39]
	ds_read_b64_tr_b16 v[208:209], v147 offset:0x45c0
	ds_read_b64_tr_b16 v[210:211], v147 offset:0x67c0
	v_mfma_f32_16x16x32_bf16 v[28:31], v[112:115], v[214:217], v[28:31]
	ds_read_b64_tr_b16 v[214:215], v147 offset:0x1e0
	ds_read_b64_tr_b16 v[216:217], v147 offset:0x23e0
	v_mfma_f32_16x16x32_bf16 v[28:31], v[116:119], v[218:221], v[28:31]
	ds_read_b64_tr_b16 v[218:219], v147 offset:0x45e0
	ds_read_b64_tr_b16 v[220:221], v147 offset:0x67e0
	s_waitcnt lgkmcnt(8)
	v_mfma_f32_16x16x32_bf16 v[44:47], v[112:115], v[120:123], v[44:47]
	s_waitcnt lgkmcnt(0)
	v_mfma_f32_16x16x32_bf16 v[44:47], v[116:119], v[124:127], v[44:47]
	v_mfma_f32_16x16x32_bf16 v[52:55], v[112:115], v[154:157], v[52:55]
	v_mfma_f32_16x16x32_bf16 v[52:55], v[116:119], v[158:161], v[52:55]
	v_mfma_f32_16x16x32_bf16 v[32:35], v[112:115], v[194:197], v[32:35]
	v_mfma_f32_16x16x32_bf16 v[32:35], v[116:119], v[208:211], v[32:35]
	v_mfma_f32_16x16x32_bf16 v[24:27], v[112:115], v[214:217], v[24:27]
	v_mfma_f32_16x16x32_bf16 v[24:27], v[116:119], v[218:221], v[24:27]

.LBB0_402:
	v_add_u32_e32 v147, s7, v169
	ds_read_b128 v[128:131], v147 offset:0
	ds_read_b128 v[132:135], v147 offset:64
	ds_read_b128 v[136:139], v147 offset:0x80
	ds_read_b128 v[140:143], v147 offset:0xc0
	ds_read_b128 v[154:157], v147 offset:0x1200
	ds_read_b128 v[158:161], v147 offset:0x1240
	ds_read_b128 v[194:197], v147 offset:0x1280
	ds_read_b128 v[208:211], v147 offset:0x12c0
	s_waitcnt lgkmcnt(4)
	s_nop 0
	v_mfma_f32_16x16x32_bf16 v[128:131], v[128:131], v[12:15], 0
	v_mfma_f32_16x16x32_bf16 v[128:131], v[132:135], v[16:19], v[128:131]
	v_mfma_f32_16x16x32_bf16 v[128:131], v[136:139], v[20:23], v[128:131]
	ds_read_b128 v[136:139], v147 offset:0x2400
	v_mfma_f32_16x16x32_bf16 v[128:131], v[140:143], v[8:11], v[128:131]
	ds_read_b128 v[140:143], v147 offset:0x2440
	ds_read_b128 v[214:217], v147 offset:0x2480
	ds_read_b128 v[218:221], v147 offset:0x24c0
	s_waitcnt lgkmcnt(4)
	v_mfma_f32_16x16x32_bf16 v[132:135], v[154:157], v[12:15], 0
	ds_read_b128 v[154:157], v147 offset:0x3600
	v_mfma_f32_16x16x32_bf16 v[132:135], v[158:161], v[16:19], v[132:135]
	ds_read_b128 v[158:161], v147 offset:0x3640
	v_mfma_f32_16x16x32_bf16 v[132:135], v[194:197], v[20:23], v[132:135]
	ds_read_b128 v[194:197], v147 offset:0x3680
	v_mfma_f32_16x16x32_bf16 v[132:135], v[208:211], v[8:11], v[132:135]
	ds_read_b128 v[208:211], v147 offset:0x36c0
	s_waitcnt lgkmcnt(4)
	v_mfma_f32_16x16x32_bf16 v[136:139], v[136:139], v[12:15], 0
	s_waitcnt lgkmcnt(0)
	v_mfma_f32_16x16x32_bf16 v[136:139], v[140:143], v[16:19], v[136:139]
	v_mfma_f32_16x16x32_bf16 v[136:139], v[214:217], v[20:23], v[136:139]
	v_mfma_f32_16x16x32_bf16 v[140:143], v[218:221], v[8:11], v[136:139]
	v_mfma_f32_16x16x32_bf16 v[136:139], v[154:157], v[12:15], 0
	s_andn2_b64 vcc, exec, s[4:5]
	v_mfma_f32_16x16x32_bf16 v[136:139], v[158:161], v[16:19], v[136:139]
	v_mfma_f32_16x16x32_bf16 v[136:139], v[194:197], v[20:23], v[136:139]
	v_mfma_f32_16x16x32_bf16 v[136:139], v[208:211], v[8:11], v[136:139]
	s_cbranch_vccnz .LBB0_404
	v_add_u32_e32 v147, s1, v167
	v_cvt_pk_bf16_f32 v112, v112, v113
	v_cvt_pk_bf16_f32 v113, v114, v115
	v_cvt_pk_bf16_f32 v114, v116, v117
	v_cvt_pk_bf16_f32 v115, v118, v119
	v_cvt_pk_bf16_f32 v116, v120, v121
	v_cvt_pk_bf16_f32 v117, v122, v123
	v_cvt_pk_bf16_f32 v118, v124, v125
	v_cvt_pk_bf16_f32 v119, v126, v127
	ds_read_b64_tr_b16 v[120:121], v147 offset:0
	ds_read_b64_tr_b16 v[122:123], v147 offset:0x2200
	ds_read_b64_tr_b16 v[124:125], v147 offset:0x4400
	ds_read_b64_tr_b16 v[126:127], v147 offset:0x6600
	ds_read_b64_tr_b16 v[154:155], v147 offset:32
	ds_read_b64_tr_b16 v[156:157], v147 offset:0x2220
	ds_read_b64_tr_b16 v[158:159], v147 offset:0x4420
	ds_read_b64_tr_b16 v[160:161], v147 offset:0x6620
	ds_read_b64_tr_b16 v[194:195], v147 offset:64
	ds_read_b64_tr_b16 v[196:197], v147 offset:0x2240
	ds_read_b64_tr_b16 v[208:209], v147 offset:0x4440
	ds_read_b64_tr_b16 v[210:211], v147 offset:0x6640
	ds_read_b64_tr_b16 v[214:215], v147 offset:0x60
	ds_read_b64_tr_b16 v[216:217], v147 offset:0x2260
	ds_read_b64_tr_b16 v[218:219], v147 offset:0x4460
	ds_read_b64_tr_b16 v[220:221], v147 offset:0x6660
	s_waitcnt lgkmcnt(8)
	s_nop 0
	v_mfma_f32_16x16x32_bf16 v[84:87], v[112:115], v[120:123], v[84:87]
	ds_read_b64_tr_b16 v[120:121], v147 offset:0x80
	ds_read_b64_tr_b16 v[122:123], v147 offset:0x2280
	v_mfma_f32_16x16x32_bf16 v[84:87], v[116:119], v[124:127], v[84:87]
	ds_read_b64_tr_b16 v[124:125], v147 offset:0x4480
	ds_read_b64_tr_b16 v[126:127], v147 offset:0x6680
	v_mfma_f32_16x16x32_bf16 v[80:83], v[112:115], v[154:157], v[80:83]
	ds_read_b64_tr_b16 v[154:155], v147 offset:0xa0
	ds_read_b64_tr_b16 v[156:157], v147 offset:0x22a0
	v_mfma_f32_16x16x32_bf16 v[80:83], v[116:119], v[158:161], v[80:83]
	ds_read_b64_tr_b16 v[158:159], v147 offset:0x44a0
	ds_read_b64_tr_b16 v[160:161], v147 offset:0x66a0
	s_waitcnt lgkmcnt(8)
	v_mfma_f32_16x16x32_bf16 v[76:79], v[112:115], v[194:197], v[76:79]
	ds_read_b64_tr_b16 v[194:195], v147 offset:0xc0
	ds_read_b64_tr_b16 v[196:197], v147 offset:0x22c0
	v_mfma_f32_16x16x32_bf16 v[76:79], v[116:119], v[208:211], v[76:79]
	ds_read_b64_tr_b16 v[208:209], v147 offset:0x44c0
	ds_read_b64_tr_b16 v[210:211], v147 offset:0x66c0
	v_mfma_f32_16x16x32_bf16 v[72:75], v[112:115], v[214:217], v[72:75]
	ds_read_b64_tr_b16 v[214:215], v147 offset:0xe0
	ds_read_b64_tr_b16 v[216:217], v147 offset:0x22e0
	v_mfma_f32_16x16x32_bf16 v[72:75], v[116:119], v[218:221], v[72:75]
	ds_read_b64_tr_b16 v[218:219], v147 offset:0x44e0
	ds_read_b64_tr_b16 v[220:221], v147 offset:0x66e0
	s_waitcnt lgkmcnt(8)
	v_mfma_f32_16x16x32_bf16 v[68:71], v[112:115], v[120:123], v[68:71]
	ds_read_b64_tr_b16 v[120:121], v147 offset:0x100
	ds_read_b64_tr_b16 v[122:123], v147 offset:0x2300
	v_mfma_f32_16x16x32_bf16 v[68:71], v[116:119], v[124:127], v[68:71]
	ds_read_b64_tr_b16 v[124:125], v147 offset:0x4500
	ds_read_b64_tr_b16 v[126:127], v147 offset:0x6700
	v_mfma_f32_16x16x32_bf16 v[64:67], v[112:115], v[154:157], v[64:67]
	ds_read_b64_tr_b16 v[154:155], v147 offset:0x120
	ds_read_b64_tr_b16 v[156:157], v147 offset:0x2320
	v_mfma_f32_16x16x32_bf16 v[64:67], v[116:119], v[158:161], v[64:67]
	ds_read_b64_tr_b16 v[158:159], v147 offset:0x4520
	ds_read_b64_tr_b16 v[160:161], v147 offset:0x6720
	s_waitcnt lgkmcnt(8)
	v_mfma_f32_16x16x32_bf16 v[60:63], v[112:115], v[194:197], v[60:63]
	ds_read_b64_tr_b16 v[194:195], v147 offset:0x140
	ds_read_b64_tr_b16 v[196:197], v147 offset:0x2340
	v_mfma_f32_16x16x32_bf16 v[60:63], v[116:119], v[208:211], v[60:63]
	ds_read_b64_tr_b16 v[208:209], v147 offset:0x4540
	ds_read_b64_tr_b16 v[210:211], v147 offset:0x6740
	v_mfma_f32_16x16x32_bf16 v[56:59], v[112:115], v[214:217], v[56:59]
	ds_read_b64_tr_b16 v[214:215], v147 offset:0x160
	ds_read_b64_tr_b16 v[216:217], v147 offset:0x2360
	v_mfma_f32_16x16x32_bf16 v[56:59], v[116:119], v[218:221], v[56:59]
	ds_read_b64_tr_b16 v[218:219], v147 offset:0x4560
	ds_read_b64_tr_b16 v[220:221], v147 offset:0x6760
	s_waitcnt lgkmcnt(8)
	v_mfma_f32_16x16x32_bf16 v[48:51], v[112:115], v[120:123], v[48:51]
	ds_read_b64_tr_b16 v[120:121], v147 offset:0x180
	ds_read_b64_tr_b16 v[122:123], v147 offset:0x2380
	v_mfma_f32_16x16x32_bf16 v[48:51], v[116:119], v[124:127], v[48:51]
	ds_read_b64_tr_b16 v[124:125], v147 offset:0x4580
	ds_read_b64_tr_b16 v[126:127], v147 offset:0x6780
	v_mfma_f32_16x16x32_bf16 v[40:43], v[112:115], v[154:157], v[40:43]
	ds_read_b64_tr_b16 v[154:155], v147 offset:0x1a0
	ds_read_b64_tr_b16 v[156:157], v147 offset:0x23a0
	v_mfma_f32_16x16x32_bf16 v[40:43], v[116:119], v[158:161], v[40:43]
	ds_read_b64_tr_b16 v[158:159], v147 offset:0x45a0
	ds_read_b64_tr_b16 v[160:161], v147 offset:0x67a0
	s_waitcnt lgkmcnt(8)
	v_mfma_f32_16x16x32_bf16 v[36:39], v[112:115], v[194:197], v[36:39]
	ds_read_b64_tr_b16 v[194:195], v147 offset:0x1c0
	ds_read_b64_tr_b16 v[196:197], v147 offset:0x23c0
	v_mfma_f32_16x16x32_bf16 v[36:39], v[116:119], v[208:211], v[36:39]
	ds_read_b64_tr_b16 v[208:209], v147 offset:0x45c0
	ds_read_b64_tr_b16 v[210:211], v147 offset:0x67c0
	v_mfma_f32_16x16x32_bf16 v[28:31], v[112:115], v[214:217], v[28:31]
	ds_read_b64_tr_b16 v[214:215], v147 offset:0x1e0
	ds_read_b64_tr_b16 v[216:217], v147 offset:0x23e0
	v_mfma_f32_16x16x32_bf16 v[28:31], v[116:119], v[218:221], v[28:31]
	ds_read_b64_tr_b16 v[218:219], v147 offset:0x45e0
	ds_read_b64_tr_b16 v[220:221], v147 offset:0x67e0
	s_waitcnt lgkmcnt(8)
	v_mfma_f32_16x16x32_bf16 v[44:47], v[112:115], v[120:123], v[44:47]
	s_waitcnt lgkmcnt(0)
	v_mfma_f32_16x16x32_bf16 v[44:47], v[116:119], v[124:127], v[44:47]
	v_mfma_f32_16x16x32_bf16 v[52:55], v[112:115], v[154:157], v[52:55]
	v_mfma_f32_16x16x32_bf16 v[52:55], v[116:119], v[158:161], v[52:55]
	v_mfma_f32_16x16x32_bf16 v[32:35], v[112:115], v[194:197], v[32:35]
	v_mfma_f32_16x16x32_bf16 v[32:35], v[116:119], v[208:211], v[32:35]
	v_mfma_f32_16x16x32_bf16 v[24:27], v[112:115], v[214:217], v[24:27]
	v_mfma_f32_16x16x32_bf16 v[24:27], v[116:119], v[218:221], v[24:27]

.LBB0_461:
	s_mul_i32 s7, s1, 0xd000
	s_mov_b32 s59, s1
	s_add_i32 s1, s7, 0
	s_add_i32 s2, s29, 0xffffff81
	v_add_u32_e32 v128, s1, v4
	s_ashr_i32 s3, s2, 31
	s_waitcnt lgkmcnt(0)
	s_barrier
	s_waitcnt vmcnt(5)
	ds_write_b128 v128, v[92:95]
	s_waitcnt vmcnt(4)
	ds_write_b128 v128, v[88:91] offset:128
	v_add_u32_e32 v88, s1, v219
	s_lshl_b64 s[2:3], s[2:3], 12
	s_waitcnt vmcnt(3)
	ds_write_b128 v88, v[96:99] offset:18432
	s_waitcnt vmcnt(2)
	ds_write_b128 v88, v[100:103] offset:18560
	s_waitcnt vmcnt(1)
	ds_write_b128 v88, v[104:107] offset:18688
	s_waitcnt vmcnt(0)
	ds_write_b128 v88, v[108:111] offset:18816
	v_lshl_add_u64 v[88:89], v[148:149], 0, s[2:3]
	v_lshl_add_u64 v[108:109], v[150:151], 0, s[2:3]
	global_load_dwordx4 v[92:95], v[88:89], off offset:256
	s_nop 0
	global_load_dwordx4 v[88:91], v[88:89], off offset:384
	s_nop 0
	global_load_dwordx4 v[96:99], v[108:109], off
	global_load_dwordx4 v[100:103], v[108:109], off offset:128
	global_load_dwordx4 v[104:107], v[108:109], off offset:256
	s_nop 0
	global_load_dwordx4 v[108:111], v[108:109], off offset:384
	s_mul_i32 s1, s28, 0xd000
	v_add_u32_e32 v147, s1, v220
	ds_read_b128 v[128:131], v147 offset:0
	ds_read_b128 v[132:135], v147 offset:64
	ds_read_b128 v[136:139], v147 offset:0x80
	ds_read_b128 v[140:143], v147 offset:0xc0
	ds_read_b128 v[154:157], v147 offset:0x1200
	ds_read_b128 v[158:161], v147 offset:0x1240
	ds_read_b128 v[236:239], v147 offset:0x1280
	ds_read_b128 v[240:243], v147 offset:0x12c0
	s_waitcnt lgkmcnt(4)
	s_nop 0
	v_mfma_f32_16x16x32_bf16 v[128:131], v[128:131], v[48:51], 0
	v_mfma_f32_16x16x32_bf16 v[128:131], v[132:135], v[52:55], v[128:131]
	v_mfma_f32_16x16x32_bf16 v[128:131], v[136:139], v[56:59], v[128:131]
	ds_read_b128 v[136:139], v147 offset:0x2400
	v_mfma_f32_16x16x32_bf16 v[128:131], v[140:143], v[84:87], v[128:131]
	ds_read_b128 v[140:143], v147 offset:0x2440
	ds_read_b128 v[244:247], v147 offset:0x2480
	ds_read_b128 v[248:251], v147 offset:0x24c0
	s_waitcnt lgkmcnt(4)
	v_mfma_f32_16x16x32_bf16 v[132:135], v[154:157], v[48:51], 0
	ds_read_b128 v[154:157], v147 offset:0x3600
	v_mfma_f32_16x16x32_bf16 v[132:135], v[158:161], v[52:55], v[132:135]
	ds_read_b128 v[158:161], v147 offset:0x3640
	v_mfma_f32_16x16x32_bf16 v[132:135], v[236:239], v[56:59], v[132:135]
	ds_read_b128 v[236:239], v147 offset:0x3680
	v_mfma_f32_16x16x32_bf16 v[132:135], v[240:243], v[84:87], v[132:135]
	ds_read_b128 v[240:243], v147 offset:0x36c0
	s_waitcnt lgkmcnt(4)
	v_mfma_f32_16x16x32_bf16 v[136:139], v[136:139], v[48:51], 0
	s_waitcnt lgkmcnt(0)
	v_mfma_f32_16x16x32_bf16 v[136:139], v[140:143], v[52:55], v[136:139]
	v_mfma_f32_16x16x32_bf16 v[136:139], v[244:247], v[56:59], v[136:139]
	v_mfma_f32_16x16x32_bf16 v[140:143], v[248:251], v[84:87], v[136:139]
	v_mfma_f32_16x16x32_bf16 v[136:139], v[154:157], v[48:51], 0
	s_and_b64 vcc, exec, s[44:45]
	s_mul_i32 s9, s58, 0xd000
	v_mfma_f32_16x16x32_bf16 v[136:139], v[158:161], v[52:55], v[136:139]
	v_mfma_f32_16x16x32_bf16 v[136:139], v[236:239], v[56:59], v[136:139]
	v_mfma_f32_16x16x32_bf16 v[136:139], v[240:243], v[84:87], v[136:139]
	s_cbranch_vccnz .LBB0_463
	s_mul_i32 s2, s58, 0xd000
	v_add_u32_e32 v147, s2, v217
	v_cvt_pk_bf16_f32 v112, v112, v113
	v_cvt_pk_bf16_f32 v113, v114, v115
	v_cvt_pk_bf16_f32 v114, v116, v117
	v_cvt_pk_bf16_f32 v115, v118, v119
	v_cvt_pk_bf16_f32 v116, v120, v121
	v_cvt_pk_bf16_f32 v117, v122, v123
	v_cvt_pk_bf16_f32 v118, v124, v125
	v_cvt_pk_bf16_f32 v119, v126, v127
	ds_read_b64_tr_b16 v[120:121], v147 offset:0
	ds_read_b64_tr_b16 v[122:123], v147 offset:0x2200
	ds_read_b64_tr_b16 v[124:125], v147 offset:0x4400
	ds_read_b64_tr_b16 v[126:127], v147 offset:0x6600
	ds_read_b64_tr_b16 v[154:155], v147 offset:32
	ds_read_b64_tr_b16 v[156:157], v147 offset:0x2220
	ds_read_b64_tr_b16 v[158:159], v147 offset:0x4420
	ds_read_b64_tr_b16 v[160:161], v147 offset:0x6620
	ds_read_b64_tr_b16 v[236:237], v147 offset:64
	ds_read_b64_tr_b16 v[238:239], v147 offset:0x2240
	ds_read_b64_tr_b16 v[240:241], v147 offset:0x4440
	ds_read_b64_tr_b16 v[242:243], v147 offset:0x6640
	ds_read_b64_tr_b16 v[244:245], v147 offset:0x60
	ds_read_b64_tr_b16 v[246:247], v147 offset:0x2260
	ds_read_b64_tr_b16 v[248:249], v147 offset:0x4460
	ds_read_b64_tr_b16 v[250:251], v147 offset:0x6660
	s_waitcnt lgkmcnt(8)
	s_nop 0
	v_mfma_f32_16x16x32_bf16 v[80:83], v[112:115], v[120:123], v[80:83]
	ds_read_b64_tr_b16 v[120:121], v147 offset:0x80
	ds_read_b64_tr_b16 v[122:123], v147 offset:0x2280
	v_mfma_f32_16x16x32_bf16 v[80:83], v[116:119], v[124:127], v[80:83]
	ds_read_b64_tr_b16 v[124:125], v147 offset:0x4480
	ds_read_b64_tr_b16 v[126:127], v147 offset:0x6680
	v_mfma_f32_16x16x32_bf16 v[76:79], v[112:115], v[154:157], v[76:79]
	ds_read_b64_tr_b16 v[154:155], v147 offset:0xa0
	ds_read_b64_tr_b16 v[156:157], v147 offset:0x22a0
	v_mfma_f32_16x16x32_bf16 v[76:79], v[116:119], v[158:161], v[76:79]
	ds_read_b64_tr_b16 v[158:159], v147 offset:0x44a0
	ds_read_b64_tr_b16 v[160:161], v147 offset:0x66a0
	s_waitcnt lgkmcnt(8)
	v_mfma_f32_16x16x32_bf16 v[72:75], v[112:115], v[236:239], v[72:75]
	ds_read_b64_tr_b16 v[236:237], v147 offset:0xc0
	ds_read_b64_tr_b16 v[238:239], v147 offset:0x22c0
	v_mfma_f32_16x16x32_bf16 v[72:75], v[116:119], v[240:243], v[72:75]
	ds_read_b64_tr_b16 v[240:241], v147 offset:0x44c0
	ds_read_b64_tr_b16 v[242:243], v147 offset:0x66c0
	v_mfma_f32_16x16x32_bf16 v[68:71], v[112:115], v[244:247], v[68:71]
	ds_read_b64_tr_b16 v[244:245], v147 offset:0xe0
	ds_read_b64_tr_b16 v[246:247], v147 offset:0x22e0
	v_mfma_f32_16x16x32_bf16 v[68:71], v[116:119], v[248:251], v[68:71]
	ds_read_b64_tr_b16 v[248:249], v147 offset:0x44e0
	ds_read_b64_tr_b16 v[250:251], v147 offset:0x66e0
	s_waitcnt lgkmcnt(8)
	v_mfma_f32_16x16x32_bf16 v[64:67], v[112:115], v[120:123], v[64:67]
	ds_read_b64_tr_b16 v[120:121], v147 offset:0x100
	ds_read_b64_tr_b16 v[122:123], v147 offset:0x2300
	v_mfma_f32_16x16x32_bf16 v[64:67], v[116:119], v[124:127], v[64:67]
	ds_read_b64_tr_b16 v[124:125], v147 offset:0x4500
	ds_read_b64_tr_b16 v[126:127], v147 offset:0x6700
	v_mfma_f32_16x16x32_bf16 v[60:63], v[112:115], v[154:157], v[60:63]
	ds_read_b64_tr_b16 v[154:155], v147 offset:0x120
	ds_read_b64_tr_b16 v[156:157], v147 offset:0x2320
	v_mfma_f32_16x16x32_bf16 v[60:63], v[116:119], v[158:161], v[60:63]
	ds_read_b64_tr_b16 v[158:159], v147 offset:0x4520
	ds_read_b64_tr_b16 v[160:161], v147 offset:0x6720
	s_waitcnt lgkmcnt(8)
	v_mfma_f32_16x16x32_bf16 v[44:47], v[112:115], v[236:239], v[44:47]
	ds_read_b64_tr_b16 v[236:237], v147 offset:0x140
	ds_read_b64_tr_b16 v[238:239], v147 offset:0x2340
	v_mfma_f32_16x16x32_bf16 v[44:47], v[116:119], v[240:243], v[44:47]
	ds_read_b64_tr_b16 v[240:241], v147 offset:0x4540
	ds_read_b64_tr_b16 v[242:243], v147 offset:0x6740
	v_mfma_f32_16x16x32_bf16 v[40:43], v[112:115], v[244:247], v[40:43]
	ds_read_b64_tr_b16 v[244:245], v147 offset:0x160
	ds_read_b64_tr_b16 v[246:247], v147 offset:0x2360
	v_mfma_f32_16x16x32_bf16 v[40:43], v[116:119], v[248:251], v[40:43]
	ds_read_b64_tr_b16 v[248:249], v147 offset:0x4560
	ds_read_b64_tr_b16 v[250:251], v147 offset:0x6760
	s_waitcnt lgkmcnt(8)
	v_mfma_f32_16x16x32_bf16 v[32:35], v[112:115], v[120:123], v[32:35]
	ds_read_b64_tr_b16 v[120:121], v147 offset:0x180
	ds_read_b64_tr_b16 v[122:123], v147 offset:0x2380
	v_mfma_f32_16x16x32_bf16 v[32:35], v[116:119], v[124:127], v[32:35]
	ds_read_b64_tr_b16 v[124:125], v147 offset:0x4580
	ds_read_b64_tr_b16 v[126:127], v147 offset:0x6780
	v_mfma_f32_16x16x32_bf16 v[24:27], v[112:115], v[154:157], v[24:27]
	ds_read_b64_tr_b16 v[154:155], v147 offset:0x1a0
	ds_read_b64_tr_b16 v[156:157], v147 offset:0x23a0
	v_mfma_f32_16x16x32_bf16 v[24:27], v[116:119], v[158:161], v[24:27]
	ds_read_b64_tr_b16 v[158:159], v147 offset:0x45a0
	ds_read_b64_tr_b16 v[160:161], v147 offset:0x67a0
	s_waitcnt lgkmcnt(8)
	v_mfma_f32_16x16x32_bf16 v[20:23], v[112:115], v[236:239], v[20:23]
	ds_read_b64_tr_b16 v[236:237], v147 offset:0x1c0
	ds_read_b64_tr_b16 v[238:239], v147 offset:0x23c0
	v_mfma_f32_16x16x32_bf16 v[20:23], v[116:119], v[240:243], v[20:23]
	ds_read_b64_tr_b16 v[240:241], v147 offset:0x45c0
	ds_read_b64_tr_b16 v[242:243], v147 offset:0x67c0
	v_mfma_f32_16x16x32_bf16 v[12:15], v[112:115], v[244:247], v[12:15]
	ds_read_b64_tr_b16 v[244:245], v147 offset:0x1e0
	ds_read_b64_tr_b16 v[246:247], v147 offset:0x23e0
	v_mfma_f32_16x16x32_bf16 v[12:15], v[116:119], v[248:251], v[12:15]
	ds_read_b64_tr_b16 v[248:249], v147 offset:0x45e0
	ds_read_b64_tr_b16 v[250:251], v147 offset:0x67e0
	s_waitcnt lgkmcnt(8)
	v_mfma_f32_16x16x32_bf16 v[28:31], v[112:115], v[120:123], v[28:31]
	s_waitcnt lgkmcnt(0)
	v_mfma_f32_16x16x32_bf16 v[28:31], v[116:119], v[124:127], v[28:31]
	v_mfma_f32_16x16x32_bf16 v[36:39], v[112:115], v[154:157], v[36:39]
	v_mfma_f32_16x16x32_bf16 v[36:39], v[116:119], v[158:161], v[36:39]
	v_mfma_f32_16x16x32_bf16 v[16:19], v[112:115], v[236:239], v[16:19]
	v_mfma_f32_16x16x32_bf16 v[16:19], v[116:119], v[240:243], v[16:19]
	v_mfma_f32_16x16x32_bf16 v[8:11], v[112:115], v[244:247], v[8:11]
	v_mfma_f32_16x16x32_bf16 v[8:11], v[116:119], v[248:251], v[8:11]

.LBB0_477:
	v_add_u32_e32 v147, s7, v220
	ds_read_b128 v[128:131], v147 offset:0
	ds_read_b128 v[132:135], v147 offset:64
	ds_read_b128 v[136:139], v147 offset:0x80
	ds_read_b128 v[140:143], v147 offset:0xc0
	ds_read_b128 v[154:157], v147 offset:0x1200
	ds_read_b128 v[158:161], v147 offset:0x1240
	ds_read_b128 v[236:239], v147 offset:0x1280
	ds_read_b128 v[240:243], v147 offset:0x12c0
	s_waitcnt lgkmcnt(4)
	s_nop 0
	v_mfma_f32_16x16x32_bf16 v[128:131], v[128:131], v[48:51], 0
	v_mfma_f32_16x16x32_bf16 v[128:131], v[132:135], v[52:55], v[128:131]
	v_mfma_f32_16x16x32_bf16 v[128:131], v[136:139], v[56:59], v[128:131]
	ds_read_b128 v[136:139], v147 offset:0x2400
	v_mfma_f32_16x16x32_bf16 v[128:131], v[140:143], v[84:87], v[128:131]
	ds_read_b128 v[140:143], v147 offset:0x2440
	ds_read_b128 v[244:247], v147 offset:0x2480
	ds_read_b128 v[248:251], v147 offset:0x24c0
	s_waitcnt lgkmcnt(4)
	v_mfma_f32_16x16x32_bf16 v[132:135], v[154:157], v[48:51], 0
	ds_read_b128 v[154:157], v147 offset:0x3600
	v_mfma_f32_16x16x32_bf16 v[132:135], v[158:161], v[52:55], v[132:135]
	ds_read_b128 v[158:161], v147 offset:0x3640
	v_mfma_f32_16x16x32_bf16 v[132:135], v[236:239], v[56:59], v[132:135]
	ds_read_b128 v[236:239], v147 offset:0x3680
	v_mfma_f32_16x16x32_bf16 v[132:135], v[240:243], v[84:87], v[132:135]
	ds_read_b128 v[240:243], v147 offset:0x36c0
	s_waitcnt lgkmcnt(4)
	v_mfma_f32_16x16x32_bf16 v[136:139], v[136:139], v[48:51], 0
	s_waitcnt lgkmcnt(0)
	v_mfma_f32_16x16x32_bf16 v[136:139], v[140:143], v[52:55], v[136:139]
	v_mfma_f32_16x16x32_bf16 v[136:139], v[244:247], v[56:59], v[136:139]
	v_mfma_f32_16x16x32_bf16 v[140:143], v[248:251], v[84:87], v[136:139]
	v_mfma_f32_16x16x32_bf16 v[136:139], v[154:157], v[48:51], 0
	s_andn2_b64 vcc, exec, s[4:5]
	v_mfma_f32_16x16x32_bf16 v[136:139], v[158:161], v[52:55], v[136:139]
	v_mfma_f32_16x16x32_bf16 v[136:139], v[236:239], v[56:59], v[136:139]
	v_mfma_f32_16x16x32_bf16 v[136:139], v[240:243], v[84:87], v[136:139]
	s_cbranch_vccnz .LBB0_479
	v_add_u32_e32 v147, s1, v217
	v_cvt_pk_bf16_f32 v112, v112, v113
	v_cvt_pk_bf16_f32 v113, v114, v115
	v_cvt_pk_bf16_f32 v114, v116, v117
	v_cvt_pk_bf16_f32 v115, v118, v119
	v_cvt_pk_bf16_f32 v116, v120, v121
	v_cvt_pk_bf16_f32 v117, v122, v123
	v_cvt_pk_bf16_f32 v118, v124, v125
	v_cvt_pk_bf16_f32 v119, v126, v127
	ds_read_b64_tr_b16 v[120:121], v147 offset:0
	ds_read_b64_tr_b16 v[122:123], v147 offset:0x2200
	ds_read_b64_tr_b16 v[124:125], v147 offset:0x4400
	ds_read_b64_tr_b16 v[126:127], v147 offset:0x6600
	ds_read_b64_tr_b16 v[154:155], v147 offset:32
	ds_read_b64_tr_b16 v[156:157], v147 offset:0x2220
	ds_read_b64_tr_b16 v[158:159], v147 offset:0x4420
	ds_read_b64_tr_b16 v[160:161], v147 offset:0x6620
	ds_read_b64_tr_b16 v[236:237], v147 offset:64
	ds_read_b64_tr_b16 v[238:239], v147 offset:0x2240
	ds_read_b64_tr_b16 v[240:241], v147 offset:0x4440
	ds_read_b64_tr_b16 v[242:243], v147 offset:0x6640
	ds_read_b64_tr_b16 v[244:245], v147 offset:0x60
	ds_read_b64_tr_b16 v[246:247], v147 offset:0x2260
	ds_read_b64_tr_b16 v[248:249], v147 offset:0x4460
	ds_read_b64_tr_b16 v[250:251], v147 offset:0x6660
	s_waitcnt lgkmcnt(8)
	s_nop 0
	v_mfma_f32_16x16x32_bf16 v[80:83], v[112:115], v[120:123], v[80:83]
	ds_read_b64_tr_b16 v[120:121], v147 offset:0x80
	ds_read_b64_tr_b16 v[122:123], v147 offset:0x2280
	v_mfma_f32_16x16x32_bf16 v[80:83], v[116:119], v[124:127], v[80:83]
	ds_read_b64_tr_b16 v[124:125], v147 offset:0x4480
	ds_read_b64_tr_b16 v[126:127], v147 offset:0x6680
	v_mfma_f32_16x16x32_bf16 v[76:79], v[112:115], v[154:157], v[76:79]
	ds_read_b64_tr_b16 v[154:155], v147 offset:0xa0
	ds_read_b64_tr_b16 v[156:157], v147 offset:0x22a0
	v_mfma_f32_16x16x32_bf16 v[76:79], v[116:119], v[158:161], v[76:79]
	ds_read_b64_tr_b16 v[158:159], v147 offset:0x44a0
	ds_read_b64_tr_b16 v[160:161], v147 offset:0x66a0
	s_waitcnt lgkmcnt(8)
	v_mfma_f32_16x16x32_bf16 v[72:75], v[112:115], v[236:239], v[72:75]
	ds_read_b64_tr_b16 v[236:237], v147 offset:0xc0
	ds_read_b64_tr_b16 v[238:239], v147 offset:0x22c0
	v_mfma_f32_16x16x32_bf16 v[72:75], v[116:119], v[240:243], v[72:75]
	ds_read_b64_tr_b16 v[240:241], v147 offset:0x44c0
	ds_read_b64_tr_b16 v[242:243], v147 offset:0x66c0
	v_mfma_f32_16x16x32_bf16 v[68:71], v[112:115], v[244:247], v[68:71]
	ds_read_b64_tr_b16 v[244:245], v147 offset:0xe0
	ds_read_b64_tr_b16 v[246:247], v147 offset:0x22e0
	v_mfma_f32_16x16x32_bf16 v[68:71], v[116:119], v[248:251], v[68:71]
	ds_read_b64_tr_b16 v[248:249], v147 offset:0x44e0
	ds_read_b64_tr_b16 v[250:251], v147 offset:0x66e0
	s_waitcnt lgkmcnt(8)
	v_mfma_f32_16x16x32_bf16 v[64:67], v[112:115], v[120:123], v[64:67]
	ds_read_b64_tr_b16 v[120:121], v147 offset:0x100
	ds_read_b64_tr_b16 v[122:123], v147 offset:0x2300
	v_mfma_f32_16x16x32_bf16 v[64:67], v[116:119], v[124:127], v[64:67]
	ds_read_b64_tr_b16 v[124:125], v147 offset:0x4500
	ds_read_b64_tr_b16 v[126:127], v147 offset:0x6700
	v_mfma_f32_16x16x32_bf16 v[60:63], v[112:115], v[154:157], v[60:63]
	ds_read_b64_tr_b16 v[154:155], v147 offset:0x120
	ds_read_b64_tr_b16 v[156:157], v147 offset:0x2320
	v_mfma_f32_16x16x32_bf16 v[60:63], v[116:119], v[158:161], v[60:63]
	ds_read_b64_tr_b16 v[158:159], v147 offset:0x4520
	ds_read_b64_tr_b16 v[160:161], v147 offset:0x6720
	s_waitcnt lgkmcnt(8)
	v_mfma_f32_16x16x32_bf16 v[44:47], v[112:115], v[236:239], v[44:47]
	ds_read_b64_tr_b16 v[236:237], v147 offset:0x140
	ds_read_b64_tr_b16 v[238:239], v147 offset:0x2340
	v_mfma_f32_16x16x32_bf16 v[44:47], v[116:119], v[240:243], v[44:47]
	ds_read_b64_tr_b16 v[240:241], v147 offset:0x4540
	ds_read_b64_tr_b16 v[242:243], v147 offset:0x6740
	v_mfma_f32_16x16x32_bf16 v[40:43], v[112:115], v[244:247], v[40:43]
	ds_read_b64_tr_b16 v[244:245], v147 offset:0x160
	ds_read_b64_tr_b16 v[246:247], v147 offset:0x2360
	v_mfma_f32_16x16x32_bf16 v[40:43], v[116:119], v[248:251], v[40:43]
	ds_read_b64_tr_b16 v[248:249], v147 offset:0x4560
	ds_read_b64_tr_b16 v[250:251], v147 offset:0x6760
	s_waitcnt lgkmcnt(8)
	v_mfma_f32_16x16x32_bf16 v[32:35], v[112:115], v[120:123], v[32:35]
	ds_read_b64_tr_b16 v[120:121], v147 offset:0x180
	ds_read_b64_tr_b16 v[122:123], v147 offset:0x2380
	v_mfma_f32_16x16x32_bf16 v[32:35], v[116:119], v[124:127], v[32:35]
	ds_read_b64_tr_b16 v[124:125], v147 offset:0x4580
	ds_read_b64_tr_b16 v[126:127], v147 offset:0x6780
	v_mfma_f32_16x16x32_bf16 v[24:27], v[112:115], v[154:157], v[24:27]
	ds_read_b64_tr_b16 v[154:155], v147 offset:0x1a0
	ds_read_b64_tr_b16 v[156:157], v147 offset:0x23a0
	v_mfma_f32_16x16x32_bf16 v[24:27], v[116:119], v[158:161], v[24:27]
	ds_read_b64_tr_b16 v[158:159], v147 offset:0x45a0
	ds_read_b64_tr_b16 v[160:161], v147 offset:0x67a0
	s_waitcnt lgkmcnt(8)
	v_mfma_f32_16x16x32_bf16 v[20:23], v[112:115], v[236:239], v[20:23]
	ds_read_b64_tr_b16 v[236:237], v147 offset:0x1c0
	ds_read_b64_tr_b16 v[238:239], v147 offset:0x23c0
	v_mfma_f32_16x16x32_bf16 v[20:23], v[116:119], v[240:243], v[20:23]
	ds_read_b64_tr_b16 v[240:241], v147 offset:0x45c0
	ds_read_b64_tr_b16 v[242:243], v147 offset:0x67c0
	v_mfma_f32_16x16x32_bf16 v[12:15], v[112:115], v[244:247], v[12:15]
	ds_read_b64_tr_b16 v[244:245], v147 offset:0x1e0
	ds_read_b64_tr_b16 v[246:247], v147 offset:0x23e0
	v_mfma_f32_16x16x32_bf16 v[12:15], v[116:119], v[248:251], v[12:15]
	ds_read_b64_tr_b16 v[248:249], v147 offset:0x45e0
	ds_read_b64_tr_b16 v[250:251], v147 offset:0x67e0
	s_waitcnt lgkmcnt(8)
	v_mfma_f32_16x16x32_bf16 v[28:31], v[112:115], v[120:123], v[28:31]
	s_waitcnt lgkmcnt(0)
	v_mfma_f32_16x16x32_bf16 v[28:31], v[116:119], v[124:127], v[28:31]
	v_mfma_f32_16x16x32_bf16 v[36:39], v[112:115], v[154:157], v[36:39]
	v_mfma_f32_16x16x32_bf16 v[36:39], v[116:119], v[158:161], v[36:39]
	v_mfma_f32_16x16x32_bf16 v[16:19], v[112:115], v[236:239], v[16:19]
	v_mfma_f32_16x16x32_bf16 v[16:19], v[116:119], v[240:243], v[16:19]
	v_mfma_f32_16x16x32_bf16 v[8:11], v[112:115], v[244:247], v[8:11]
	v_mfma_f32_16x16x32_bf16 v[8:11], v[116:119], v[248:251], v[8:11]

.LBB0_494:
	s_waitcnt lgkmcnt(0)
	s_barrier
	v_add_u32_e32 v2, s9, v220
	s_waitcnt vmcnt(4)
	ds_read_b128 v[88:91], v2 offset:0
	ds_read_b128 v[92:95], v2 offset:64
	s_waitcnt vmcnt(3)
	ds_read_b128 v[96:99], v2 offset:0x80
	s_waitcnt vmcnt(2)
	ds_read_b128 v[100:103], v2 offset:0xc0
	s_waitcnt vmcnt(1)
	ds_read_b128 v[104:107], v2 offset:0x1200
	s_waitcnt vmcnt(0)
	ds_read_b128 v[108:111], v2 offset:0x1240
	ds_read_b128 v[128:131], v2 offset:0x1280
	ds_read_b128 v[132:135], v2 offset:0x12c0
	s_waitcnt lgkmcnt(4)
	v_mfma_f32_16x16x32_bf16 v[88:91], v[88:91], v[48:51], 0
	v_mfma_f32_16x16x32_bf16 v[88:91], v[92:95], v[52:55], v[88:91]
	v_mfma_f32_16x16x32_bf16 v[88:91], v[96:99], v[56:59], v[88:91]
	ds_read_b128 v[96:99], v2 offset:0x2400
	v_mfma_f32_16x16x32_bf16 v[88:91], v[100:103], v[84:87], v[88:91]
	ds_read_b128 v[100:103], v2 offset:0x2440
	ds_read_b128 v[136:139], v2 offset:0x2480
	ds_read_b128 v[140:143], v2 offset:0x24c0
	s_waitcnt lgkmcnt(4)
	v_mfma_f32_16x16x32_bf16 v[92:95], v[104:107], v[48:51], 0
	ds_read_b128 v[104:107], v2 offset:0x3600
	v_mfma_f32_16x16x32_bf16 v[92:95], v[108:111], v[52:55], v[92:95]
	ds_read_b128 v[108:111], v2 offset:0x3640
	v_mfma_f32_16x16x32_bf16 v[92:95], v[128:131], v[56:59], v[92:95]
	ds_read_b128 v[128:131], v2 offset:0x3680
	v_mfma_f32_16x16x32_bf16 v[92:95], v[132:135], v[84:87], v[92:95]
	ds_read_b128 v[132:135], v2 offset:0x36c0
	s_waitcnt lgkmcnt(4)
	v_mfma_f32_16x16x32_bf16 v[96:99], v[96:99], v[48:51], 0
	s_waitcnt lgkmcnt(0)
	v_mfma_f32_16x16x32_bf16 v[96:99], v[100:103], v[52:55], v[96:99]
	v_mfma_f32_16x16x32_bf16 v[96:99], v[136:139], v[56:59], v[96:99]
	v_mfma_f32_16x16x32_bf16 v[96:99], v[140:143], v[84:87], v[96:99]
	v_mfma_f32_16x16x32_bf16 v[48:51], v[104:107], v[48:51], 0
	s_andn2_b64 vcc, exec, s[44:45]
	v_mfma_f32_16x16x32_bf16 v[48:51], v[108:111], v[52:55], v[48:51]
	v_mfma_f32_16x16x32_bf16 v[48:51], v[128:131], v[56:59], v[48:51]
	v_mfma_f32_16x16x32_bf16 v[52:55], v[132:135], v[84:87], v[48:51]
	s_cbranch_vccz .LBB0_496
	v_add_u32_e32 v2, s7, v217
	v_cvt_pk_bf16_f32 v48, v112, v113
	v_cvt_pk_bf16_f32 v49, v114, v115
	v_cvt_pk_bf16_f32 v50, v116, v117
	v_cvt_pk_bf16_f32 v51, v118, v119
	v_cvt_pk_bf16_f32 v56, v120, v121
	v_cvt_pk_bf16_f32 v57, v122, v123
	v_cvt_pk_bf16_f32 v58, v124, v125
	v_cvt_pk_bf16_f32 v59, v126, v127
	ds_read_b64_tr_b16 v[84:85], v2 offset:0
	ds_read_b64_tr_b16 v[86:87], v2 offset:0x2200
	ds_read_b64_tr_b16 v[100:101], v2 offset:0x4400
	ds_read_b64_tr_b16 v[102:103], v2 offset:0x6600
	ds_read_b64_tr_b16 v[104:105], v2 offset:32
	ds_read_b64_tr_b16 v[106:107], v2 offset:0x2220
	ds_read_b64_tr_b16 v[108:109], v2 offset:0x4420
	ds_read_b64_tr_b16 v[110:111], v2 offset:0x6620
	ds_read_b64_tr_b16 v[112:113], v2 offset:64
	ds_read_b64_tr_b16 v[114:115], v2 offset:0x2240
	ds_read_b64_tr_b16 v[116:117], v2 offset:0x4440
	ds_read_b64_tr_b16 v[118:119], v2 offset:0x6640
	ds_read_b64_tr_b16 v[120:121], v2 offset:0x60
	ds_read_b64_tr_b16 v[122:123], v2 offset:0x2260
	ds_read_b64_tr_b16 v[124:125], v2 offset:0x4460
	ds_read_b64_tr_b16 v[126:127], v2 offset:0x6660
	s_waitcnt lgkmcnt(8)
	s_nop 4
	v_mfma_f32_16x16x32_bf16 v[80:83], v[48:51], v[84:87], v[80:83]
	ds_read_b64_tr_b16 v[84:85], v2 offset:0x80
	ds_read_b64_tr_b16 v[86:87], v2 offset:0x2280
	v_mfma_f32_16x16x32_bf16 v[80:83], v[56:59], v[100:103], v[80:83]
	ds_read_b64_tr_b16 v[100:101], v2 offset:0x4480
	ds_read_b64_tr_b16 v[102:103], v2 offset:0x6680
	v_mfma_f32_16x16x32_bf16 v[76:79], v[48:51], v[104:107], v[76:79]
	ds_read_b64_tr_b16 v[104:105], v2 offset:0xa0
	ds_read_b64_tr_b16 v[106:107], v2 offset:0x22a0
	v_mfma_f32_16x16x32_bf16 v[76:79], v[56:59], v[108:111], v[76:79]
	ds_read_b64_tr_b16 v[108:109], v2 offset:0x44a0
	ds_read_b64_tr_b16 v[110:111], v2 offset:0x66a0
	s_waitcnt lgkmcnt(8)
	v_mfma_f32_16x16x32_bf16 v[72:75], v[48:51], v[112:115], v[72:75]
	ds_read_b64_tr_b16 v[112:113], v2 offset:0xc0
	ds_read_b64_tr_b16 v[114:115], v2 offset:0x22c0
	v_mfma_f32_16x16x32_bf16 v[72:75], v[56:59], v[116:119], v[72:75]
	ds_read_b64_tr_b16 v[116:117], v2 offset:0x44c0
	ds_read_b64_tr_b16 v[118:119], v2 offset:0x66c0
	v_mfma_f32_16x16x32_bf16 v[68:71], v[48:51], v[120:123], v[68:71]
	ds_read_b64_tr_b16 v[120:121], v2 offset:0xe0
	ds_read_b64_tr_b16 v[122:123], v2 offset:0x22e0
	v_mfma_f32_16x16x32_bf16 v[68:71], v[56:59], v[124:127], v[68:71]
	ds_read_b64_tr_b16 v[124:125], v2 offset:0x44e0
	ds_read_b64_tr_b16 v[126:127], v2 offset:0x66e0
	s_waitcnt lgkmcnt(8)
	v_mfma_f32_16x16x32_bf16 v[64:67], v[48:51], v[84:87], v[64:67]
	ds_read_b64_tr_b16 v[84:85], v2 offset:0x100
	ds_read_b64_tr_b16 v[86:87], v2 offset:0x2300
	v_mfma_f32_16x16x32_bf16 v[64:67], v[56:59], v[100:103], v[64:67]
	ds_read_b64_tr_b16 v[100:101], v2 offset:0x4500
	ds_read_b64_tr_b16 v[102:103], v2 offset:0x6700
	v_mfma_f32_16x16x32_bf16 v[60:63], v[48:51], v[104:107], v[60:63]
	ds_read_b64_tr_b16 v[104:105], v2 offset:0x120
	ds_read_b64_tr_b16 v[106:107], v2 offset:0x2320
	v_mfma_f32_16x16x32_bf16 v[60:63], v[56:59], v[108:111], v[60:63]
	ds_read_b64_tr_b16 v[108:109], v2 offset:0x4520
	ds_read_b64_tr_b16 v[110:111], v2 offset:0x6720
	s_waitcnt lgkmcnt(8)
	v_mfma_f32_16x16x32_bf16 v[44:47], v[48:51], v[112:115], v[44:47]
	ds_read_b64_tr_b16 v[112:113], v2 offset:0x140
	ds_read_b64_tr_b16 v[114:115], v2 offset:0x2340
	v_mfma_f32_16x16x32_bf16 v[44:47], v[56:59], v[116:119], v[44:47]
	ds_read_b64_tr_b16 v[116:117], v2 offset:0x4540
	ds_read_b64_tr_b16 v[118:119], v2 offset:0x6740
	v_mfma_f32_16x16x32_bf16 v[40:43], v[48:51], v[120:123], v[40:43]
	ds_read_b64_tr_b16 v[120:121], v2 offset:0x160
	ds_read_b64_tr_b16 v[122:123], v2 offset:0x2360
	v_mfma_f32_16x16x32_bf16 v[40:43], v[56:59], v[124:127], v[40:43]
	ds_read_b64_tr_b16 v[124:125], v2 offset:0x4560
	ds_read_b64_tr_b16 v[126:127], v2 offset:0x6760
	s_waitcnt lgkmcnt(8)
	v_mfma_f32_16x16x32_bf16 v[32:35], v[48:51], v[84:87], v[32:35]
	ds_read_b64_tr_b16 v[84:85], v2 offset:0x180
	ds_read_b64_tr_b16 v[86:87], v2 offset:0x2380
	v_mfma_f32_16x16x32_bf16 v[32:35], v[56:59], v[100:103], v[32:35]
	ds_read_b64_tr_b16 v[100:101], v2 offset:0x4580
	ds_read_b64_tr_b16 v[102:103], v2 offset:0x6780
	v_mfma_f32_16x16x32_bf16 v[24:27], v[48:51], v[104:107], v[24:27]
	ds_read_b64_tr_b16 v[104:105], v2 offset:0x1a0
	ds_read_b64_tr_b16 v[106:107], v2 offset:0x23a0
	v_mfma_f32_16x16x32_bf16 v[24:27], v[56:59], v[108:111], v[24:27]
	ds_read_b64_tr_b16 v[108:109], v2 offset:0x45a0
	ds_read_b64_tr_b16 v[110:111], v2 offset:0x67a0
	s_waitcnt lgkmcnt(8)
	v_mfma_f32_16x16x32_bf16 v[20:23], v[48:51], v[112:115], v[20:23]
	ds_read_b64_tr_b16 v[112:113], v2 offset:0x1c0
	ds_read_b64_tr_b16 v[114:115], v2 offset:0x23c0
	v_mfma_f32_16x16x32_bf16 v[20:23], v[56:59], v[116:119], v[20:23]
	ds_read_b64_tr_b16 v[116:117], v2 offset:0x45c0
	ds_read_b64_tr_b16 v[118:119], v2 offset:0x67c0
	v_mfma_f32_16x16x32_bf16 v[12:15], v[48:51], v[120:123], v[12:15]
	ds_read_b64_tr_b16 v[120:121], v2 offset:0x1e0
	ds_read_b64_tr_b16 v[122:123], v2 offset:0x23e0
	v_mfma_f32_16x16x32_bf16 v[12:15], v[56:59], v[124:127], v[12:15]
	ds_read_b64_tr_b16 v[124:125], v2 offset:0x45e0
	ds_read_b64_tr_b16 v[126:127], v2 offset:0x67e0
	s_waitcnt lgkmcnt(8)
	v_mfma_f32_16x16x32_bf16 v[28:31], v[48:51], v[84:87], v[28:31]
	s_waitcnt lgkmcnt(0)
	v_mfma_f32_16x16x32_bf16 v[28:31], v[56:59], v[100:103], v[28:31]
	v_mfma_f32_16x16x32_bf16 v[36:39], v[48:51], v[104:107], v[36:39]
	v_mfma_f32_16x16x32_bf16 v[36:39], v[56:59], v[108:111], v[36:39]
	v_mfma_f32_16x16x32_bf16 v[16:19], v[48:51], v[112:115], v[16:19]
	v_mfma_f32_16x16x32_bf16 v[16:19], v[56:59], v[116:119], v[16:19]
	v_mfma_f32_16x16x32_bf16 v[8:11], v[48:51], v[120:123], v[8:11]
	v_mfma_f32_16x16x32_bf16 v[8:11], v[56:59], v[124:127], v[8:11]

.LBB0_516:
	v_add_u32_e32 v2, s9, v217
	v_cvt_pk_bf16_f32 v48, v48, v49
	v_cvt_pk_bf16_f32 v49, v50, v51
	v_cvt_pk_bf16_f32 v50, v56, v57
	v_cvt_pk_bf16_f32 v51, v58, v59
	v_cvt_pk_bf16_f32 v52, v84, v85
	v_cvt_pk_bf16_f32 v53, v86, v87
	v_cvt_pk_bf16_f32 v54, v100, v101
	v_cvt_pk_bf16_f32 v55, v102, v103
	ds_read_b64_tr_b16 v[56:57], v2 offset:0
	ds_read_b64_tr_b16 v[58:59], v2 offset:0x2200
	ds_read_b64_tr_b16 v[84:85], v2 offset:0x4400
	ds_read_b64_tr_b16 v[86:87], v2 offset:0x6600
	ds_read_b64_tr_b16 v[88:89], v2 offset:32
	ds_read_b64_tr_b16 v[90:91], v2 offset:0x2220
	ds_read_b64_tr_b16 v[92:93], v2 offset:0x4420
	ds_read_b64_tr_b16 v[94:95], v2 offset:0x6620
	ds_read_b64_tr_b16 v[96:97], v2 offset:64
	ds_read_b64_tr_b16 v[98:99], v2 offset:0x2240
	ds_read_b64_tr_b16 v[100:101], v2 offset:0x4440
	ds_read_b64_tr_b16 v[102:103], v2 offset:0x6640
	ds_read_b64_tr_b16 v[104:105], v2 offset:0x60
	ds_read_b64_tr_b16 v[106:107], v2 offset:0x2260
	ds_read_b64_tr_b16 v[108:109], v2 offset:0x4460
	ds_read_b64_tr_b16 v[110:111], v2 offset:0x6660
	s_waitcnt lgkmcnt(8)
	s_nop 0
	v_mfma_f32_16x16x32_bf16 v[56:59], v[48:51], v[56:59], v[80:83]
	v_mfma_f32_16x16x32_bf16 v[80:83], v[52:55], v[84:87], v[56:59]
	v_mfma_f32_16x16x32_bf16 v[56:59], v[48:51], v[88:91], v[76:79]
	v_mfma_f32_16x16x32_bf16 v[76:79], v[52:55], v[92:95], v[56:59]
	ds_read_b64_tr_b16 v[56:57], v2 offset:0x80
	ds_read_b64_tr_b16 v[58:59], v2 offset:0x2280
	ds_read_b64_tr_b16 v[84:85], v2 offset:0x4480
	ds_read_b64_tr_b16 v[86:87], v2 offset:0x6680
	ds_read_b64_tr_b16 v[88:89], v2 offset:0xa0
	ds_read_b64_tr_b16 v[90:91], v2 offset:0x22a0
	ds_read_b64_tr_b16 v[92:93], v2 offset:0x44a0
	ds_read_b64_tr_b16 v[94:95], v2 offset:0x66a0
	s_waitcnt lgkmcnt(8)
	v_mfma_f32_16x16x32_bf16 v[72:75], v[48:51], v[96:99], v[72:75]
	ds_read_b64_tr_b16 v[96:97], v2 offset:0xc0
	ds_read_b64_tr_b16 v[98:99], v2 offset:0x22c0
	v_mfma_f32_16x16x32_bf16 v[72:75], v[52:55], v[100:103], v[72:75]
	ds_read_b64_tr_b16 v[100:101], v2 offset:0x44c0
	ds_read_b64_tr_b16 v[102:103], v2 offset:0x66c0
	v_mfma_f32_16x16x32_bf16 v[68:71], v[48:51], v[104:107], v[68:71]
	ds_read_b64_tr_b16 v[104:105], v2 offset:0xe0
	ds_read_b64_tr_b16 v[106:107], v2 offset:0x22e0
	v_mfma_f32_16x16x32_bf16 v[68:71], v[52:55], v[108:111], v[68:71]
	ds_read_b64_tr_b16 v[108:109], v2 offset:0x44e0
	ds_read_b64_tr_b16 v[110:111], v2 offset:0x66e0
	s_waitcnt lgkmcnt(8)
	s_nop 2
	v_mfma_f32_16x16x32_bf16 v[56:59], v[48:51], v[56:59], v[64:67]
	v_mfma_f32_16x16x32_bf16 v[64:67], v[52:55], v[84:87], v[56:59]
	v_mfma_f32_16x16x32_bf16 v[56:59], v[48:51], v[88:91], v[60:63]
	v_mfma_f32_16x16x32_bf16 v[60:63], v[52:55], v[92:95], v[56:59]
	ds_read_b64_tr_b16 v[56:57], v2 offset:0x100
	ds_read_b64_tr_b16 v[58:59], v2 offset:0x2300
	ds_read_b64_tr_b16 v[84:85], v2 offset:0x4500
	ds_read_b64_tr_b16 v[86:87], v2 offset:0x6700
	ds_read_b64_tr_b16 v[88:89], v2 offset:0x120
	ds_read_b64_tr_b16 v[90:91], v2 offset:0x2320
	ds_read_b64_tr_b16 v[92:93], v2 offset:0x4520
	ds_read_b64_tr_b16 v[94:95], v2 offset:0x6720
	s_waitcnt lgkmcnt(8)
	v_mfma_f32_16x16x32_bf16 v[44:47], v[48:51], v[96:99], v[44:47]
	ds_read_b64_tr_b16 v[96:97], v2 offset:0x140
	ds_read_b64_tr_b16 v[98:99], v2 offset:0x2340
	v_mfma_f32_16x16x32_bf16 v[44:47], v[52:55], v[100:103], v[44:47]
	ds_read_b64_tr_b16 v[100:101], v2 offset:0x4540
	ds_read_b64_tr_b16 v[102:103], v2 offset:0x6740
	v_mfma_f32_16x16x32_bf16 v[40:43], v[48:51], v[104:107], v[40:43]
	ds_read_b64_tr_b16 v[104:105], v2 offset:0x160
	ds_read_b64_tr_b16 v[106:107], v2 offset:0x2360
	v_mfma_f32_16x16x32_bf16 v[40:43], v[52:55], v[108:111], v[40:43]
	ds_read_b64_tr_b16 v[108:109], v2 offset:0x4560
	ds_read_b64_tr_b16 v[110:111], v2 offset:0x6760
	s_waitcnt lgkmcnt(8)
	s_nop 2
	v_mfma_f32_16x16x32_bf16 v[32:35], v[48:51], v[56:59], v[32:35]
	ds_read_b64_tr_b16 v[56:57], v2 offset:0x180
	ds_read_b64_tr_b16 v[58:59], v2 offset:0x2380
	v_mfma_f32_16x16x32_bf16 v[32:35], v[52:55], v[84:87], v[32:35]
	ds_read_b64_tr_b16 v[84:85], v2 offset:0x4580
	ds_read_b64_tr_b16 v[86:87], v2 offset:0x6780
	v_mfma_f32_16x16x32_bf16 v[24:27], v[48:51], v[88:91], v[24:27]
	ds_read_b64_tr_b16 v[88:89], v2 offset:0x1a0
	ds_read_b64_tr_b16 v[90:91], v2 offset:0x23a0
	v_mfma_f32_16x16x32_bf16 v[24:27], v[52:55], v[92:95], v[24:27]
	ds_read_b64_tr_b16 v[92:93], v2 offset:0x45a0
	ds_read_b64_tr_b16 v[94:95], v2 offset:0x67a0
	s_waitcnt lgkmcnt(8)
	v_mfma_f32_16x16x32_bf16 v[20:23], v[48:51], v[96:99], v[20:23]
	ds_read_b64_tr_b16 v[96:97], v2 offset:0x1c0
	ds_read_b64_tr_b16 v[98:99], v2 offset:0x23c0
	v_mfma_f32_16x16x32_bf16 v[20:23], v[52:55], v[100:103], v[20:23]
	ds_read_b64_tr_b16 v[100:101], v2 offset:0x45c0
	ds_read_b64_tr_b16 v[102:103], v2 offset:0x67c0
	v_mfma_f32_16x16x32_bf16 v[12:15], v[48:51], v[104:107], v[12:15]
	ds_read_b64_tr_b16 v[104:105], v2 offset:0x1e0
	ds_read_b64_tr_b16 v[106:107], v2 offset:0x23e0
	v_mfma_f32_16x16x32_bf16 v[12:15], v[52:55], v[108:111], v[12:15]
	ds_read_b64_tr_b16 v[108:109], v2 offset:0x45e0
	ds_read_b64_tr_b16 v[110:111], v2 offset:0x67e0
	s_waitcnt lgkmcnt(8)
	v_mfma_f32_16x16x32_bf16 v[28:31], v[48:51], v[56:59], v[28:31]
	s_waitcnt lgkmcnt(0)
	v_mfma_f32_16x16x32_bf16 v[28:31], v[52:55], v[84:87], v[28:31]
	v_mfma_f32_16x16x32_bf16 v[36:39], v[48:51], v[88:91], v[36:39]
	v_mfma_f32_16x16x32_bf16 v[36:39], v[52:55], v[92:95], v[36:39]
	v_mfma_f32_16x16x32_bf16 v[16:19], v[48:51], v[96:99], v[16:19]
	v_mfma_f32_16x16x32_bf16 v[16:19], v[52:55], v[100:103], v[16:19]
	v_mfma_f32_16x16x32_bf16 v[8:11], v[48:51], v[104:107], v[8:11]
	v_mfma_f32_16x16x32_bf16 v[8:11], v[52:55], v[108:111], v[8:11]
	v_cmp_gt_u32_e32 vcc, 16, v214
	s_and_saveexec_b64 s[2:3], vcc
	s_cbranch_execnz .LBB0_511
	s_branch .LBB0_512
